# barrier member poll interval s_sleep 6 instead of 1 (less traffic on the counter line)
# baseline (speedup 1.0000x reference)
.LBB0_1978:
	s_and_b32 s18, s25, 0xff
	s_mov_b64 s[16:17], -1
	s_cmp_lg_u32 s18, 0
	s_mov_b64 s[18:19], -1
	s_sleep 6
	s_cbranch_scc1 .LBB0_1982
	v_mov_b64_e32 v[2:3], s[2:3]
	flat_load_dword v0, v[2:3] offset:512 sc1
	s_mov_b64 s[18:19], 0
	s_mov_b64 s[20:21], -1
	s_waitcnt vmcnt(0) lgkmcnt(0)
	v_cmp_eq_u32_e32 vcc, 0, v0
	s_and_saveexec_b64 s[22:23], vcc
	s_cmp_lt_u32 s25, 0x40001
	s_cselect_b64 s[18:19], -1, 0
	s_xor_b64 s[20:21], exec, -1
	s_and_b64 s[18:19], s[18:19], exec
	s_or_b64 exec, exec, s[22:23]
